# MLA: hand-written guard-free fast path for steady-state iterations (SGPR-base loads, rare paths out of line) + half-step stagger of wave halves + premax + LDS ring
# speedup vs baseline: 1.0155x; 1.0025x over previous
; #define FA_LOADK(t) do { _Pragma("unroll") for (int i = 0; i < KI; ++i) if (tid + 512 * i < NKC) kr[i] = *(const u32x4*)(Kb + (size_t)((t) * 64 + krow_[i]) * ldk + kc8_[i] * 8); } while (0)
; #define FA_LOADV(t) do { _Pragma("unroll") for (int i = 0; i < VI; ++i) { const int c = tid + 512 * i, cg_ = c0 + (c >> 3); vr[i] = *(const u32x4*)(Vseq + (size_t)cg_ * L + ((kv0 + 64 * ((t) + cg_)) & (L - 1)) + (c & 7) * 8); } } while (0)
; template <int DK, int DV, int MODE> ...
;     ...
;     u32x4 kr1[KI], kr2[KI], vr1[VI]; const int t1_ = ntiles > 1 ? 1 : 0, t2_ = ntiles > 2 ? 2 : ntiles - 1;
;     FA_LOADK(0); FA_LOADV(0);
; #pragma unroll
;     for (int i = 0; i < KI; ++i) if (tid + 512 * i < NKC) { kr1[i] = *(const u32x4*)(Kb + (size_t)(t1_ * 64 + krow_[i]) * ldk + kc8_[i] * 8); kr2[i] = *(const u32x4*)(Kb + (size_t)(t2_ * 64 + krow_[i]) * ldk + kc8_[i] * 8); }
; #pragma unroll
;     for (int i = 0; i < VI; ++i) { const int c = tid + 512 * i, cg_ = c0 + (c >> 3); vr1[i] = *(const u32x4*)(Vseq + (size_t)cg_ * L + ((kv0 + 64 * (t1_ + cg_)) & (L - 1)) + (c & 7) * 8); }
.LBB0_232:
	s_or_b64 exec, exec, s[66:67]
	s_ashr_i32 s61, s60, 31
	s_lshl_b64 s[22:23], s[60:61], 11
	s_add_u32 s22, s80, s22
	s_addc_u32 s23, s81, s23
	s_mov_b64 s[70:71], s[22:23]
	s_lshl_b32 s60, s19, 6
	v_ashrrev_i32_e32 v68, 3, v36
	v_add_u32_e32 v0, s60, v68
	v_mad_i64_i32 v[2:3], s[26:27], v0, s17, 0
	v_lshlrev_b32_e32 v35, 6, v0
	s_add_i32 s16, s17, -1
	v_lshl_add_u64 v[30:31], v[2:3], 1, s[22:23]
	v_and_b32_e32 v0, s16, v35
	v_lshlrev_b32_e32 v39, 3, v36
	v_lshl_add_u64 v[2:3], v[0:1], 1, v[30:31]
	v_and_b32_e32 v0, 56, v39
	v_lshlrev_b32_e32 v0, 1, v0
	v_lshl_add_u64 v[2:3], v[2:3], 0, v[0:1]
	global_load_dwordx4 v[6:9], v[2:3], off
	s_and_saveexec_b64 s[66:67], s[44:45]
	s_cbranch_execz .LBB0_234
	s_waitcnt lgkmcnt(1)
	v_add_u32_e32 v4, 64, v66
	v_mov_b64_e32 v[2:3], s[50:51]
	v_add_u32_e32 v12, 0x80, v66
	s_waitcnt lgkmcnt(0)
	v_mad_i64_i32 v[4:5], s[22:23], v4, s7, v[2:3]
	v_lshlrev_b64 v[10:11], 1, v[26:27]
	v_mad_i64_i32 v[2:3], s[22:23], v12, s7, v[2:3]
	v_lshl_add_u64 v[4:5], v[4:5], 0, v[10:11]
	v_lshl_add_u64 v[10:11], v[2:3], 0, v[10:11]
	global_load_dwordx4 v[2:5], v[4:5], off
	s_nop 0
	global_load_dwordx4 v[10:13], v[10:11], off

; #define FA_BAR do { asm volatile("s_waitcnt lgkmcnt(0)" ::: "memory"); __builtin_amdgcn_s_barrier(); asm volatile("" ::: "memory"); } while (0)
; #define FA_LOADK(t) do { _Pragma("unroll") for (int i = 0; i < KI; ++i) if (tid + 512 * i < NKC) kr[i] = *(const u32x4*)(Kb + (size_t)((t) * 64 + krow_[i]) * ldk + kc8_[i] * 8); } while (0)
; #define FA_LOADV(t) do { _Pragma("unroll") for (int i = 0; i < VI; ++i) { const int c = tid + 512 * i, cg_ = c0 + (c >> 3); vr[i] = *(const u32x4*)(Vseq + (size_t)cg_ * L + ((kv0 + 64 * ((t) + cg_)) & (L - 1)) + (c & 7) * 8); } } while (0)
; template <int DK, int DV, int MODE> ...
;     ...
;   FA_LOADK(ntiles > 3 ? 3 : ntiles - 1);
;   FA_LOADV(ntiles > 2 ? 2 : ntiles - 1);
;   FA_BAR;
;   float cpos = 0.f, cneg = 0.f; if (MODE == 0) { cpos = lut[256]; cneg = lut[0]; }
;   FA_SCORE(stA, baseA, 0);
;   for (int t = 0; t < ntiles; t += 2) {
;     FA_STEP(t, stA, baseA, stB, baseB, false);
;     if (t + 1 < ntiles) FA_STEP(t + 1, stB, baseB, stA, baseA, true);
;   }
.LBB0_248:
	s_or_b64 exec, exec, s[66:67]
	v_add_u32_e32 v2, 0x80, v35
	v_and_b32_e32 v2, s16, v2
	v_mov_b32_e32 v3, v1
	v_lshl_add_u64 v[2:3], v[2:3], 1, v[30:31]
	v_lshl_add_u64 v[2:3], v[2:3], 0, v[0:1]
	global_load_dwordx4 v[130:133], v[2:3], off
	s_waitcnt lgkmcnt(0)
	s_barrier
	v_mov_b32_e32 v2, s39
	s_add_i32 s18, 0, 0x1f400
	ds_read_b32 v158, v2
	v_mov_b32_e32 v2, s18
	ds_read_b32 v159, v2
	s_movk_i32 s6, 0x99
	v_cmp_lt_i32_e32 vcc, s6, v34
	s_movk_i32 s6, 0xff87
	v_lshl_add_u32 v18, v33, 4, 0
	s_waitcnt lgkmcnt(1)
	v_cndmask_b32_e32 v2, 0, v158, vcc
	v_cmp_gt_i32_e32 vcc, s6, v34
	s_movk_i32 s6, 0xd0
	v_mad_u32_u24 v160, v32, s6, v18
	s_waitcnt lgkmcnt(0)
	v_cndmask_b32_e32 v34, v2, v159, vcc
	ds_read_b128 v[2:5], v160
	ds_read_b128 v[6:9], v160 offset:32
	v_mov_b32_e32 v35, v34
	v_mov_b32_e32 v36, v34
	v_mov_b32_e32 v37, v34
	v_mov_b32_e32 v38, v34
	v_mov_b32_e32 v39, v34
	v_mov_b32_e32 v40, v34
	v_mov_b32_e32 v41, v34
	v_mov_b32_e32 v42, v34
	v_mov_b32_e32 v43, v34
	v_mov_b32_e32 v44, v34
	v_mov_b32_e32 v45, v34
	v_mov_b32_e32 v46, v34
	v_mov_b32_e32 v47, v34
	v_mov_b32_e32 v48, v34
	v_mov_b32_e32 v49, v34
	v_and_b32_e32 v19, 64, v221
	v_lshl_add_u64 v[136:137], v[30:31], 0, v[0:1]
	s_waitcnt lgkmcnt(1)
	v_mfma_f32_32x32x16_bf16 v[50:65], v[2:5], v[98:101], v[34:49]
	v_xor_b32_e32 v0, 32, v221
	v_add_u32_e32 v19, 64, v19
	v_cmp_lt_i32_e32 vcc, v0, v19
	v_mov_b32_e32 v161, 0
	s_lshr_b32 s17, s17, 6
	v_cndmask_b32_e32 v0, v221, v0, vcc
	v_lshlrev_b32_e32 v162, 2, v0
	s_waitcnt lgkmcnt(0)
	v_mfma_f32_32x32x16_bf16 v[50:65], v[6:9], v[102:105], v[50:65]
	ds_read_b128 v[2:5], v160 offset:64
	ds_read_b128 v[6:9], v160 offset:96
	v_lshl_add_u32 v0, v33, 2, v152
	v_sub_u32_e32 v0, v0, v32
	v_subrev_u32_e32 v164, s20, v0
	v_lshlrev_b32_e32 v0, 6, v68
	s_mov_b32 s18, 0
	v_mad_u32_u24 v163, v32, s56, v18
	s_waitcnt lgkmcnt(1)
	v_mfma_f32_32x32x16_bf16 v[50:65], v[2:5], v[106:109], v[50:65]
	v_subrev_u32_e32 v165, s20, v152
	v_lshl_add_u32 v166, s19, 12, v0
	v_mov_b32_e32 v143, 0xff800000
	s_mov_b32 s19, 5
	v_mov_b32_e32 v18, 0
	v_mov_b32_e32 v19, v161
	v_mov_b32_e32 v20, v161
	s_waitcnt lgkmcnt(0)
	v_mfma_f32_32x32x16_bf16 v[50:65], v[6:9], v[110:113], v[50:65]
	ds_read_b128 v[2:5], v160 offset:128
	ds_read_b128 v[6:9], v160 offset:160
	v_mov_b32_e32 v21, v161
	v_mov_b32_e32 v22, v161
	v_mov_b32_e32 v23, v161
	v_mov_b32_e32 v24, v161
	v_mov_b32_e32 v25, v161
	v_mov_b32_e32 v30, v161
	s_waitcnt lgkmcnt(1)
	v_mfma_f32_32x32x16_bf16 v[50:65], v[2:5], v[114:117], v[50:65]
	ds_read_b128 v[2:5], v160 offset:6656
	v_mov_b32_e32 v31, v161
	v_mov_b32_e32 v32, v161
	v_mov_b32_e32 v33, v161
	v_mov_b32_e32 v142, 0
	s_waitcnt lgkmcnt(0)
	v_mfma_f32_32x32x16_bf16 v[34:49], v[2:5], v[98:101], v[34:49]
	v_mfma_f32_32x32x16_bf16 v[50:65], v[6:9], v[118:121], v[50:65]
	ds_read_b128 v[6:9], v160 offset:6688
	ds_read_b128 v[10:13], v160 offset:6720
	ds_read_b128 v[14:17], v160 offset:6752
	ds_read_b128 v[2:5], v160 offset:6784
	ds_read_b128 v[70:73], v160 offset:6816
	s_waitcnt lgkmcnt(4)
	v_mfma_f32_32x32x16_bf16 v[34:49], v[6:9], v[102:105], v[34:49]
	v_mov_b64_e32 v[6:7], s[48:49]
	v_mad_i64_i32 v[8:9], s[22:23], v66, s7, v[6:7]
	v_mad_i64_i32 v[6:7], s[22:23], v67, s7, v[6:7]
	v_lshl_add_u64 v[8:9], v[26:27], 1, v[8:9]
	v_lshl_add_u64 v[6:7], v[28:29], 1, v[6:7]
	s_waitcnt lgkmcnt(3)
	v_mfma_f32_32x32x16_bf16 v[34:49], v[10:13], v[106:109], v[34:49]
	v_lshl_add_u64 v[138:139], s[80:81], 0, v[8:9]
	v_lshl_add_u64 v[140:141], s[80:81], 0, v[6:7]
	v_subrev_u32_e32 v222, s48, v8
	v_subrev_u32_e32 v223, s48, v6
	s_add_u32 s86, s80, s48
	s_addc_u32 s87, s81, s49
	s_add_u32 s86, s86, s40
	s_addc_u32 s87, s87, s41
	s_add_u32 s86, s86, 0xe0c0000
	s_addc_u32 s87, s87, 0
	v_mov_b32_e32 v26, v161
	v_mov_b32_e32 v27, v161
	v_mov_b32_e32 v28, v161
	v_mov_b32_e32 v29, v161
	v_mov_b32_e32 v6, v161
	s_waitcnt lgkmcnt(2)
	v_mfma_f32_32x32x16_bf16 v[34:49], v[14:17], v[110:113], v[34:49]
	v_mov_b32_e32 v7, v161
	v_mov_b32_e32 v8, v161
	v_mov_b32_e32 v9, v161
	v_mov_b32_e32 v10, v161
	v_mov_b32_e32 v11, v161
	v_mov_b32_e32 v12, v161
	v_mov_b32_e32 v13, v161
	s_waitcnt lgkmcnt(1)
	v_mfma_f32_32x32x16_bf16 v[34:49], v[2:5], v[114:117], v[34:49]
	v_mov_b32_e32 v2, v161
	v_mov_b32_e32 v3, v161
	v_mov_b32_e32 v4, v161
	v_mov_b32_e32 v5, v161
	v_mov_b32_e32 v14, v161
	v_mov_b32_e32 v15, v161
	v_mov_b32_e32 v16, v161
	s_waitcnt lgkmcnt(0)
	v_mfma_f32_32x32x16_bf16 v[34:49], v[70:73], v[118:121], v[34:49]
	v_mov_b32_e32 v17, v161
	v_subrev_u32_e32 v224, s70, v136
	v_lshlrev_b32_e32 v225, 1, v166
	v_add_u32_e32 v225, 0x180, v225
	v_add_u32_e32 v226, 0x80, v225
	v_add_u32_e32 v229, 0xd000, v157
	s_lshl_b32 s69, s16, 1
	s_or_b32 s69, s69, 1
	s_branch .LBB0_251
.Lmla_fast:
	s_add_i32 s22, s19, -2
	s_and_b32 s20, s22, 3
	s_mulk_i32 s20, 0x3400
	v_add3_u32 v0, s20, v153, v154
	s_mul_i32 s84, s18, 0xc00
	s_add_u32 s62, s86, s84
	s_addc_u32 s63, s87, 0
	s_waitcnt vmcnt(0)
	ds_write_b128 v0, v[122:125]
	s_cmp_lg_u32 s32, 0
	s_cbranch_scc1 .Lf_a1
	v_add3_u32 v0, s20, v155, v156
	ds_write_b128 v0, v[126:129]
	s_nop 1
	global_load_dwordx4 v[126:129], v223, s[62:63]
.Lf_a1:
	s_add_i32 s20, s19, -3
	s_and_b32 s21, s20, 2
	s_mulk_i32 s21, 0x2400
	v_add_u32_e32 v0, s21, v229
	ds_write2_b64 v0, v[130:131], v[132:133] offset1:2
	s_add_i32 s23, s19, -1
	global_load_dwordx4 v[122:125], v222, s[62:63]
	v_lshl_add_u32 v0, s18, 1, v225
	v_and_or_b32 v0, v0, s69, v224
	global_load_dwordx4 v[130:133], v0, s[70:71]
	v_pk_add_f32 v[66:67], v[142:143], v[174:175]
	s_nop 0
	v_cmp_gt_f32_e32 vcc, v66, v67
	s_cbranch_vccnz .Lf_resc_a
.Lf_ra:
	v_sub_f32_e32 v0, v143, v142
	v_cmp_neq_f32_e32 vcc, 0, v0
	s_cbranch_vccnz .Lf_delta_a
; #define LAS __attribute__((address_space(3)))
; DI float fexp2(float x) { return __builtin_amdgcn_exp2f(x); }
; template <int DK, int DV, int MODE> ...
;     ...
;   auto part1 = [&](f32x16 (&st)[2], float mbase, int t) __attribute__((always_inline)) {
;     if (MODE == 0) {
;       const int d0 = rel0 + 64 * t;
;       if (!(d0 - 31 >= 91) && !(d0 + 63 <= -91)) {
;         const int rb_ = d0 - r + 4 * hh + 128;
; #pragma unroll
;         for (int kb = 0; kb < 2; ++kb)
; #pragma unroll
;           for (int i = 0; i < 16; ++i) { int idx = rb_ + 32 * kb + (i & 3) + 8 * (i >> 2); idx = idx < 0 ? 0 : (idx > 256 ? 256 : idx); st[kb][i] += lut[idx]; }
;       }
;     } else {
;       const int ka = ka0 + t;
;       const LAS unsigned char* rp = (const LAS unsigned char*)lut + (ka - ri + 7) * 128;
; #pragma unroll
;       for (int q = 0; q < 8; ++q) { unsigned wv = nacolp[q]; asm volatile("" : "+v"(wv));
; #pragma unroll
;     ...
;   auto part2 = [&](f32x16 (&st)[2], int t) __attribute__((always_inline)) {
;     float ps0 = 0.f, ps1 = 0.f, ps2 = 0.f, ps3 = 0.f;
; #pragma unroll
;     for (int kb = 0; kb < 2; ++kb)
; #pragma unroll
;       for (int i = 0; i < 16; i += 4) {
;         const float p0 = fexp2(st[kb][i]), p1 = fexp2(st[kb][i + 1]), p2 = fexp2(st[kb][i + 2]), p3 = fexp2(st[kb][i + 3]);
;         st[kb][i] = p0; st[kb][i + 1] = p1; st[kb][i + 2] = p2; st[kb][i + 3] = p3; ps0 += p0; ps1 += p1; ps2 += p2; ps3 += p3;
;       }
;     lsum += (ps0 + ps1) + (ps2 + ps3);
;     bf16x8 pf[2][2];
; #pragma unroll
;     for (int kb = 0; kb < 2; ++kb)
; #pragma unroll
;       for (int s = 0; s < 2; ++s) { u32x4 pp; pp.x = cvt_pk(st[kb][8 * s], st[kb][8 * s + 1]); pp.y = cvt_pk(st[kb][8 * s + 2], st[kb][8 * s + 3]); pp.z = cvt_pk(st[kb][8 * s + 4], st[kb][8 * s + 5]); pp.w = cvt_pk(st[kb][8 * s + 6], st[kb][8 * s + 7]); pf[kb][s] = __builtin_bit_cast(bf16x8, pp); }
; #pragma unroll
;     for (int db = 0; db < DV / 32; ++db)
; #pragma unroll
;       for (int kb = 0; kb < 2; ++kb)
; #pragma unroll
;         for (int s = 0; s < 2; ++s) {
;           if (MODE == 1 && ((kb == 1 && s == 1 && cwu == 0) || (kb == 0 && s == 0 && cwu != 0))) continue;
;           const bf16x8 vf = *(const LAS bf16x8*)(lds + ATT_VB + (t & 3) * VBUF + (32 * db + r) * VSTR + (2 * kb + s) * 32 + hh * 16);
;           O[db] = __builtin_amdgcn_mfma_f32_32x32x16_bf16(vf, pf[kb][s], O[db], 0, 0, 0);
;         }
;   };
.Lf_da:
	s_cmp_eq_u32 s32, 0
	s_cbranch_scc1 .Lfb_a0
	s_waitcnt lgkmcnt(0)
	s_barrier
.Lfb_a0:
	s_setprio 1
	s_add_i32 s25, s19, -4
	s_and_b32 s21, s25, 3
	s_mul_i32 s26, s21, 0x3400
	s_and_b32 s23, s23, 2
	v_add_u32_e32 v252, s26, v160
	s_mul_i32 s26, s23, 0x2400
	ds_read_b128 v[196:199], v252
	ds_read_b128 v[200:203], v252 offset:32
	ds_read_b128 v[216:219], v252 offset:64
	ds_read_b128 v[230:233], v252 offset:96
	ds_read_b128 v[234:237], v252 offset:128
	ds_read_b128 v[244:247], v252 offset:160
	v_add_u32_e32 v243, s26, v163
	v_add_u32_e32 v0, 64, v167
	v_cmp_gt_i32_e32 vcc, s78, v0
	v_exp_f32_e32 v50, v50
	v_exp_f32_e32 v51, v51
	v_cndmask_b32_e32 v66, 0, v158, vcc
	v_cmp_lt_i32_e32 vcc, s77, v0
	v_exp_f32_e32 v52, v52
	v_exp_f32_e32 v53, v53
	v_cndmask_b32_e32 v0, v66, v159, vcc
	v_cmp_neq_f32_e32 vcc, s53, v143
	v_exp_f32_e32 v54, v54
	v_exp_f32_e32 v55, v55
	v_cndmask_b32_e32 v144, 0, v143, vcc
	v_sub_f32_e32 v66, v0, v144
	v_mov_b32_e32 v67, v66
	v_mov_b32_e32 v68, v66
	v_mov_b32_e32 v69, v66
	v_mov_b32_e32 v70, v66
	v_mov_b32_e32 v71, v66
	v_mov_b32_e32 v72, v66
	v_mov_b32_e32 v73, v66
	v_mov_b32_e32 v74, v66
	v_mov_b32_e32 v75, v66
	v_mov_b32_e32 v76, v66
	v_mov_b32_e32 v77, v66
	v_mov_b32_e32 v78, v66
	v_mov_b32_e32 v79, v66
	v_mov_b32_e32 v80, v66
	v_mov_b32_e32 v81, v66
	v_exp_f32_e32 v56, v56
	v_exp_f32_e32 v57, v57
	s_waitcnt lgkmcnt(5)
	v_mfma_f32_32x32x16_bf16 v[82:97], v[196:199], v[98:101], v[66:81]
	ds_read_b128 v[196:199], v252 offset:6656
	v_exp_f32_e32 v58, v58
	v_exp_f32_e32 v59, v59
	v_exp_f32_e32 v60, v60
	v_exp_f32_e32 v61, v61
	s_waitcnt lgkmcnt(5)
	v_mfma_f32_32x32x16_bf16 v[82:97], v[200:203], v[102:105], v[82:97]
	ds_read_b128 v[200:203], v252 offset:6688
	v_exp_f32_e32 v62, v62
	v_exp_f32_e32 v63, v63
	v_exp_f32_e32 v64, v64
	v_exp_f32_e32 v65, v65
	s_waitcnt lgkmcnt(5)
	v_mfma_f32_32x32x16_bf16 v[82:97], v[216:219], v[106:109], v[82:97]
	ds_read_b128 v[216:219], v252 offset:6720
	v_exp_f32_e32 v34, v34
	v_exp_f32_e32 v35, v35
	v_cvt_pk_bf16_f32 v168, v50, v51
	v_exp_f32_e32 v36, v36
	s_waitcnt lgkmcnt(5)
	v_mfma_f32_32x32x16_bf16 v[82:97], v[230:233], v[110:113], v[82:97]
	ds_read_b128 v[230:233], v252 offset:6752
	v_exp_f32_e32 v37, v37
	v_cvt_pk_bf16_f32 v169, v52, v53
	v_exp_f32_e32 v38, v38
	v_exp_f32_e32 v39, v39
	s_waitcnt lgkmcnt(5)
	v_mfma_f32_32x32x16_bf16 v[82:97], v[234:237], v[114:117], v[82:97]
	ds_read_b128 v[234:237], v252 offset:6784
	v_cvt_pk_bf16_f32 v170, v54, v55
	v_exp_f32_e32 v40, v40
	v_exp_f32_e32 v41, v41
	v_cvt_pk_bf16_f32 v171, v56, v57
	v_exp_f32_e32 v42, v42
	s_waitcnt lgkmcnt(5)
	v_mfma_f32_32x32x16_bf16 v[82:97], v[244:247], v[118:121], v[82:97]
	ds_read_b128 v[244:247], v252 offset:6816
	v_exp_f32_e32 v43, v43
	v_cvt_pk_bf16_f32 v180, v58, v59
	v_exp_f32_e32 v44, v44
	v_exp_f32_e32 v45, v45
	s_waitcnt lgkmcnt(5)
	v_mfma_f32_32x32x16_bf16 v[66:81], v[196:199], v[98:101], v[66:81]
	ds_read_b128 v[196:199], v243 offset:53248
	v_cvt_pk_bf16_f32 v181, v60, v61
	v_exp_f32_e32 v46, v46
	v_exp_f32_e32 v47, v47
	v_cvt_pk_bf16_f32 v182, v62, v63
	v_exp_f32_e32 v48, v48
	s_waitcnt lgkmcnt(5)
	v_mfma_f32_32x32x16_bf16 v[66:81], v[200:203], v[102:105], v[66:81]
	ds_read_b128 v[200:203], v243 offset:57856
	v_exp_f32_e32 v49, v49
	v_cvt_pk_bf16_f32 v183, v64, v65
	v_add_f32_e32 v172, v50, v54
	v_add_f32_e32 v173, v51, v55
	v_add_f32_e32 v176, v52, v56
	v_add_f32_e32 v179, v53, v57
	s_waitcnt lgkmcnt(5)
	v_mfma_f32_32x32x16_bf16 v[66:81], v[216:219], v[106:109], v[66:81]
	ds_read_b128 v[216:219], v243 offset:53280
	v_add_f32_e32 v172, v58, v172
	v_add_f32_e32 v173, v59, v173
	v_add_f32_e32 v176, v60, v176
	v_add_f32_e32 v179, v61, v179
	v_add_f32_e32 v172, v62, v172
	v_add_f32_e32 v173, v63, v173
	v_add_f32_e32 v176, v64, v176
	s_waitcnt lgkmcnt(5)
	v_mfma_f32_32x32x16_bf16 v[66:81], v[230:233], v[110:113], v[66:81]
	ds_read_b128 v[230:233], v243 offset:57888
	v_add_f32_e32 v179, v65, v179
	v_cvt_pk_bf16_f32 v184, v34, v35
	v_cvt_pk_bf16_f32 v185, v36, v37
	v_cvt_pk_bf16_f32 v186, v38, v39
	v_cvt_pk_bf16_f32 v187, v40, v41
	v_cvt_pk_bf16_f32 v188, v42, v43
	v_cvt_pk_bf16_f32 v189, v44, v45
	s_waitcnt lgkmcnt(5)
	v_mfma_f32_32x32x16_bf16 v[66:81], v[234:237], v[114:117], v[66:81]
	ds_read_b128 v[234:237], v243 offset:53312
	v_cvt_pk_bf16_f32 v190, v46, v47
	v_cvt_pk_bf16_f32 v191, v48, v49
	v_add_f32_e32 v172, v34, v172
	v_add_f32_e32 v173, v35, v173
	v_add_f32_e32 v176, v36, v176
	v_add_f32_e32 v179, v37, v179
	v_add_f32_e32 v172, v38, v172
	s_waitcnt lgkmcnt(5)
	v_mfma_f32_32x32x16_bf16 v[66:81], v[244:247], v[118:121], v[66:81]
	ds_read_b128 v[244:247], v243 offset:57920
	v_add_f32_e32 v173, v39, v173
	v_add_f32_e32 v176, v40, v176
	v_add_f32_e32 v179, v41, v179
	v_add_f32_e32 v172, v42, v172
	v_add_f32_e32 v173, v43, v173
	v_add_f32_e32 v176, v44, v176
	v_add_f32_e32 v179, v45, v179
	s_waitcnt lgkmcnt(5)
	v_mfma_f32_32x32x16_bf16 v[18:33], v[196:199], v[168:171], v[18:33]
	ds_read_b128 v[196:199], v243 offset:53344
	v_add_f32_e32 v172, v46, v172
	v_add_f32_e32 v173, v47, v173
	v_add_f32_e32 v176, v48, v176
	v_add_f32_e32 v179, v49, v179
	v_add_f32_e32 v172, v172, v173
	v_add_f32_e32 v176, v176, v179
	v_max3_f32 v248, v82, v83, v84
	s_waitcnt lgkmcnt(5)
	v_mfma_f32_32x32x16_bf16 v[2:17], v[200:203], v[168:171], v[2:17]
	ds_read_b128 v[200:203], v243 offset:57952
	v_max3_f32 v249, v89, v90, v91
	v_max3_f32 v248, v248, v85, v86
	v_max3_f32 v249, v249, v92, v93
	v_max3_f32 v248, v248, v87, v88
	v_max3_f32 v249, v249, v94, v95
	s_waitcnt lgkmcnt(5)
	v_mfma_f32_32x32x16_bf16 v[18:33], v[216:219], v[180:183], v[18:33]
	v_max3_f32 v250, v66, v67, v68
	v_max3_f32 v251, v73, v74, v75
	v_max3_f32 v250, v250, v69, v70
	v_max3_f32 v251, v251, v76, v77
	v_max3_f32 v250, v250, v71, v72
	v_max3_f32 v251, v251, v78, v79
	v_max3_f32 v248, v248, v249, v96
	s_waitcnt lgkmcnt(4)
	v_mfma_f32_32x32x16_bf16 v[2:17], v[230:233], v[180:183], v[2:17]
	v_max3_f32 v250, v250, v251, v80
	v_max3_f32 v248, v248, v97, v81
	v_max_f32_e32 v248, v248, v250
	v_mov_b32_e32 v249, v248
	s_waitcnt lgkmcnt(3)
	v_mfma_f32_32x32x16_bf16 v[18:33], v[234:237], v[184:187], v[18:33]
	s_waitcnt lgkmcnt(2)
	v_mfma_f32_32x32x16_bf16 v[2:17], v[244:247], v[184:187], v[2:17]
	s_waitcnt lgkmcnt(1)
	v_mfma_f32_32x32x16_bf16 v[18:33], v[196:199], v[188:191], v[18:33]
	s_waitcnt lgkmcnt(0)
	v_mfma_f32_32x32x16_bf16 v[2:17], v[200:203], v[188:191], v[2:17]
	v_add_f32_e32 v0, v172, v176
	v_add_f32_e32 v161, v161, v0
	v_permlane32_swap_b32 v248, v249
	v_max_f32_e32 v174, v248, v249
	s_setprio 0
	s_cmp_lg_u32 s32, 0
	s_cbranch_scc1 .Lfb_a1
	s_waitcnt lgkmcnt(0)
	s_barrier
; DI float fexp2(float x) { return __builtin_amdgcn_exp2f(x); }
; template <int DK, int DV, int MODE> ...
;     ...
;     const float mabs = mx + mbase;
;     if (__any(mabs > mrun + ATT_THR)) {
;       const float mn = fmaxf(mrun, mabs), alpha = fexp2(mrun - mn); mrun = mn; lsum *= alpha;
; #pragma unroll
;       for (int db = 0; db < DV / 32; ++db)
; #pragma unroll
;         for (int i = 0; i < 16; ++i) O[db][i] *= alpha;
;     }
;     const float delta = mrun - mbase;
;     if (__any(delta != 0.f)) {
; #pragma unroll
;       for (int kb = 0; kb < 2; ++kb)
; #pragma unroll
;         for (int i = 0; i < 16; ++i) st[kb][i] -= delta;
;     }
.Lfb_a1:
	s_and_b32 s84, s23, 3
	s_mulk_i32 s84, 0x3400
	v_add3_u32 v0, s84, v153, v154
	s_add_u32 s62, s62, 0x30000
	s_addc_u32 s63, s63, 0
	s_waitcnt vmcnt(0)
	ds_write_b128 v0, v[122:125]
	s_cmp_lg_u32 s32, 0
	s_cbranch_scc1 .Lf_b1
	v_add3_u32 v0, s84, v155, v156
	ds_write_b128 v0, v[126:129]
	s_nop 1
	global_load_dwordx4 v[126:129], v223, s[62:63]
.Lf_b1:
	s_add_i32 s85, s19, -2
	s_and_b32 s85, s85, 3
	s_mulk_i32 s85, 0x2400
	v_add_u32_e32 v0, s85, v229
	ds_write2_b64 v0, v[130:131], v[132:133] offset1:2
	v_mov_b32_e32 v145, v143
	global_load_dwordx4 v[122:125], v222, s[62:63]
	v_lshl_add_u32 v0, s18, 1, v226
	v_and_or_b32 v0, v0, s69, v224
	global_load_dwordx4 v[130:133], v0, s[70:71]
	v_pk_add_f32 v[34:35], v[144:145], v[174:175]
	s_nop 0
	v_cmp_gt_f32_e32 vcc, v34, v35
	s_cbranch_vccnz .Lf_resc_b
.Lf_rb:
	v_sub_f32_e32 v0, v143, v144
	v_cmp_neq_f32_e32 vcc, 0, v0
	s_cbranch_vccnz .Lf_delta_b

; #define LAS __attribute__((address_space(3)))
; DI float fexp2(float x) { return __builtin_amdgcn_exp2f(x); }
; template <int DK, int DV, int MODE> ...
;     ...
;   auto part1 = [&](f32x16 (&st)[2], float mbase, int t) __attribute__((always_inline)) {
;     if (MODE == 0) {
;       const int d0 = rel0 + 64 * t;
;       if (!(d0 - 31 >= 91) && !(d0 + 63 <= -91)) {
;         const int rb_ = d0 - r + 4 * hh + 128;
; #pragma unroll
;         for (int kb = 0; kb < 2; ++kb)
; #pragma unroll
;           for (int i = 0; i < 16; ++i) { int idx = rb_ + 32 * kb + (i & 3) + 8 * (i >> 2); idx = idx < 0 ? 0 : (idx > 256 ? 256 : idx); st[kb][i] += lut[idx]; }
;       }
;     } else {
;       const int ka = ka0 + t;
;       const LAS unsigned char* rp = (const LAS unsigned char*)lut + (ka - ri + 7) * 128;
; #pragma unroll
;       for (int q = 0; q < 8; ++q) { unsigned wv = nacolp[q]; asm volatile("" : "+v"(wv));
; #pragma unroll
;     ...
;   auto part2 = [&](f32x16 (&st)[2], int t) __attribute__((always_inline)) {
;     float ps0 = 0.f, ps1 = 0.f, ps2 = 0.f, ps3 = 0.f;
; #pragma unroll
;     for (int kb = 0; kb < 2; ++kb)
; #pragma unroll
;       for (int i = 0; i < 16; i += 4) {
;         const float p0 = fexp2(st[kb][i]), p1 = fexp2(st[kb][i + 1]), p2 = fexp2(st[kb][i + 2]), p3 = fexp2(st[kb][i + 3]);
;         st[kb][i] = p0; st[kb][i + 1] = p1; st[kb][i + 2] = p2; st[kb][i + 3] = p3; ps0 += p0; ps1 += p1; ps2 += p2; ps3 += p3;
;       }
;     lsum += (ps0 + ps1) + (ps2 + ps3);
;     bf16x8 pf[2][2];
; #pragma unroll
;     for (int kb = 0; kb < 2; ++kb)
; #pragma unroll
;       for (int s = 0; s < 2; ++s) { u32x4 pp; pp.x = cvt_pk(st[kb][8 * s], st[kb][8 * s + 1]); pp.y = cvt_pk(st[kb][8 * s + 2], st[kb][8 * s + 3]); pp.z = cvt_pk(st[kb][8 * s + 4], st[kb][8 * s + 5]); pp.w = cvt_pk(st[kb][8 * s + 6], st[kb][8 * s + 7]); pf[kb][s] = __builtin_bit_cast(bf16x8, pp); }
; #pragma unroll
;     for (int db = 0; db < DV / 32; ++db)
; #pragma unroll
;       for (int kb = 0; kb < 2; ++kb)
; #pragma unroll
;         for (int s = 0; s < 2; ++s) {
;           if (MODE == 1 && ((kb == 1 && s == 1 && cwu == 0) || (kb == 0 && s == 0 && cwu != 0))) continue;
;           const bf16x8 vf = *(const LAS bf16x8*)(lds + ATT_VB + (t & 3) * VBUF + (32 * db + r) * VSTR + (2 * kb + s) * 32 + hh * 16);
;           O[db] = __builtin_amdgcn_mfma_f32_32x32x16_bf16(vf, pf[kb][s], O[db], 0, 0, 0);
;         }
;   };
.Lfb_b0:
	s_setprio 1
	s_and_b32 s22, s20, 2
	s_mulk_i32 s22, 0x3400
	s_mulk_i32 s21, 0x2400
	v_add_u32_e32 v252, s22, v160
	ds_read_b128 v[196:199], v252
	ds_read_b128 v[200:203], v252 offset:32
	ds_read_b128 v[216:219], v252 offset:64
	ds_read_b128 v[230:233], v252 offset:96
	ds_read_b128 v[234:237], v252 offset:128
	ds_read_b128 v[244:247], v252 offset:160
	v_add_u32_e32 v243, s21, v163
	v_add_u32_e32 v0, 0x80, v167
	v_cmp_gt_i32_e32 vcc, s78, v0
	v_exp_f32_e32 v82, v82
	v_exp_f32_e32 v83, v83
	v_cndmask_b32_e32 v34, 0, v158, vcc
	v_cmp_lt_i32_e32 vcc, s77, v0
	v_exp_f32_e32 v84, v84
	v_exp_f32_e32 v85, v85
	v_cndmask_b32_e32 v0, v34, v159, vcc
	v_cmp_neq_f32_e32 vcc, s53, v143
	v_exp_f32_e32 v86, v86
	v_exp_f32_e32 v87, v87
	v_cndmask_b32_e32 v142, 0, v143, vcc
	v_sub_f32_e32 v34, v0, v142
	v_mov_b32_e32 v35, v34
	v_mov_b32_e32 v36, v34
	v_mov_b32_e32 v37, v34
	v_mov_b32_e32 v38, v34
	v_mov_b32_e32 v39, v34
	v_mov_b32_e32 v40, v34
	v_mov_b32_e32 v41, v34
	v_mov_b32_e32 v42, v34
	v_mov_b32_e32 v43, v34
	v_mov_b32_e32 v44, v34
	v_mov_b32_e32 v45, v34
	v_mov_b32_e32 v46, v34
	v_mov_b32_e32 v47, v34
	v_mov_b32_e32 v48, v34
	v_mov_b32_e32 v49, v34
	v_exp_f32_e32 v88, v88
	v_exp_f32_e32 v89, v89
	s_waitcnt lgkmcnt(5)
	v_mfma_f32_32x32x16_bf16 v[50:65], v[196:199], v[98:101], v[34:49]
	ds_read_b128 v[196:199], v252 offset:6656
	v_exp_f32_e32 v90, v90
	v_exp_f32_e32 v91, v91
	v_exp_f32_e32 v92, v92
	v_exp_f32_e32 v93, v93
	s_waitcnt lgkmcnt(5)
	v_mfma_f32_32x32x16_bf16 v[50:65], v[200:203], v[102:105], v[50:65]
	ds_read_b128 v[200:203], v252 offset:6688
	v_exp_f32_e32 v94, v94
	v_exp_f32_e32 v95, v95
	v_exp_f32_e32 v96, v96
	v_exp_f32_e32 v97, v97
	s_waitcnt lgkmcnt(5)
	v_mfma_f32_32x32x16_bf16 v[50:65], v[216:219], v[106:109], v[50:65]
	ds_read_b128 v[216:219], v252 offset:6720
	v_exp_f32_e32 v66, v66
	v_exp_f32_e32 v67, v67
	v_cvt_pk_bf16_f32 v168, v82, v83
	v_exp_f32_e32 v68, v68
	s_waitcnt lgkmcnt(5)
	v_mfma_f32_32x32x16_bf16 v[50:65], v[230:233], v[110:113], v[50:65]
	ds_read_b128 v[230:233], v252 offset:6752
	v_exp_f32_e32 v69, v69
	v_cvt_pk_bf16_f32 v169, v84, v85
	v_exp_f32_e32 v70, v70
	v_exp_f32_e32 v71, v71
	s_waitcnt lgkmcnt(5)
	v_mfma_f32_32x32x16_bf16 v[50:65], v[234:237], v[114:117], v[50:65]
	ds_read_b128 v[234:237], v252 offset:6784
	v_cvt_pk_bf16_f32 v170, v86, v87
	v_exp_f32_e32 v72, v72
	v_exp_f32_e32 v73, v73
	v_cvt_pk_bf16_f32 v171, v88, v89
	v_exp_f32_e32 v74, v74
	s_waitcnt lgkmcnt(5)
	v_mfma_f32_32x32x16_bf16 v[50:65], v[244:247], v[118:121], v[50:65]
	ds_read_b128 v[244:247], v252 offset:6816
	v_exp_f32_e32 v75, v75
	v_cvt_pk_bf16_f32 v180, v90, v91
	v_exp_f32_e32 v76, v76
	v_exp_f32_e32 v77, v77
	s_waitcnt lgkmcnt(5)
	v_mfma_f32_32x32x16_bf16 v[34:49], v[196:199], v[98:101], v[34:49]
	ds_read_b128 v[196:199], v243 offset:53248
	v_cvt_pk_bf16_f32 v181, v92, v93
	v_exp_f32_e32 v78, v78
	v_exp_f32_e32 v79, v79
	v_cvt_pk_bf16_f32 v182, v94, v95
	v_exp_f32_e32 v80, v80
	s_waitcnt lgkmcnt(5)
	v_mfma_f32_32x32x16_bf16 v[34:49], v[200:203], v[102:105], v[34:49]
	ds_read_b128 v[200:203], v243 offset:57856
	v_exp_f32_e32 v81, v81
	v_cvt_pk_bf16_f32 v183, v96, v97
	v_add_f32_e32 v172, v82, v86
	v_add_f32_e32 v173, v83, v87
	v_add_f32_e32 v176, v84, v88
	v_add_f32_e32 v179, v85, v89
	s_waitcnt lgkmcnt(5)
	v_mfma_f32_32x32x16_bf16 v[34:49], v[216:219], v[106:109], v[34:49]
	ds_read_b128 v[216:219], v243 offset:53280
	v_add_f32_e32 v172, v90, v172
	v_add_f32_e32 v173, v91, v173
	v_add_f32_e32 v176, v92, v176
	v_add_f32_e32 v179, v93, v179
	v_add_f32_e32 v172, v94, v172
	v_add_f32_e32 v173, v95, v173
	v_add_f32_e32 v176, v96, v176
	s_waitcnt lgkmcnt(5)
	v_mfma_f32_32x32x16_bf16 v[34:49], v[230:233], v[110:113], v[34:49]
	ds_read_b128 v[230:233], v243 offset:57888
	v_add_f32_e32 v179, v97, v179
	v_cvt_pk_bf16_f32 v184, v66, v67
	v_cvt_pk_bf16_f32 v185, v68, v69
	v_cvt_pk_bf16_f32 v186, v70, v71
	v_cvt_pk_bf16_f32 v187, v72, v73
	v_cvt_pk_bf16_f32 v188, v74, v75
	v_cvt_pk_bf16_f32 v189, v76, v77
	s_waitcnt lgkmcnt(5)
	v_mfma_f32_32x32x16_bf16 v[34:49], v[234:237], v[114:117], v[34:49]
	ds_read_b128 v[234:237], v243 offset:53312
	v_cvt_pk_bf16_f32 v190, v78, v79
	v_cvt_pk_bf16_f32 v191, v80, v81
	v_add_f32_e32 v172, v66, v172
	v_add_f32_e32 v173, v67, v173
	v_add_f32_e32 v176, v68, v176
	v_add_f32_e32 v179, v69, v179
	v_add_f32_e32 v172, v70, v172
	s_waitcnt lgkmcnt(5)
	v_mfma_f32_32x32x16_bf16 v[34:49], v[244:247], v[118:121], v[34:49]
	ds_read_b128 v[244:247], v243 offset:57920
	v_add_f32_e32 v173, v71, v173
	v_add_f32_e32 v176, v72, v176
	v_add_f32_e32 v179, v73, v179
	v_add_f32_e32 v172, v74, v172
	v_add_f32_e32 v173, v75, v173
	v_add_f32_e32 v176, v76, v176
	v_add_f32_e32 v179, v77, v179
	s_waitcnt lgkmcnt(5)
	v_mfma_f32_32x32x16_bf16 v[18:33], v[196:199], v[168:171], v[18:33]
	ds_read_b128 v[196:199], v243 offset:53344
	v_add_f32_e32 v172, v78, v172
	v_add_f32_e32 v173, v79, v173
	v_add_f32_e32 v176, v80, v176
	v_add_f32_e32 v179, v81, v179
	v_add_f32_e32 v172, v172, v173
	v_add_f32_e32 v176, v176, v179
	v_max3_f32 v248, v50, v51, v52
	s_waitcnt lgkmcnt(5)
	v_mfma_f32_32x32x16_bf16 v[2:17], v[200:203], v[168:171], v[2:17]
	ds_read_b128 v[200:203], v243 offset:57952
	v_max3_f32 v249, v57, v58, v59
	v_max3_f32 v248, v248, v53, v54
	v_max3_f32 v249, v249, v60, v61
	v_max3_f32 v248, v248, v55, v56
	v_max3_f32 v249, v249, v62, v63
	s_waitcnt lgkmcnt(5)
	v_mfma_f32_32x32x16_bf16 v[18:33], v[216:219], v[180:183], v[18:33]
	v_max3_f32 v250, v34, v35, v36
	v_max3_f32 v251, v41, v42, v43
	v_max3_f32 v250, v250, v37, v38
	v_max3_f32 v251, v251, v44, v45
	v_max3_f32 v250, v250, v39, v40
	v_max3_f32 v251, v251, v46, v47
	v_max3_f32 v248, v248, v249, v64
	s_waitcnt lgkmcnt(4)
	v_mfma_f32_32x32x16_bf16 v[2:17], v[230:233], v[180:183], v[2:17]
	v_max3_f32 v250, v250, v251, v48
	v_max3_f32 v248, v248, v65, v49
	v_max_f32_e32 v248, v248, v250
	v_mov_b32_e32 v249, v248
	s_waitcnt lgkmcnt(3)
	v_mfma_f32_32x32x16_bf16 v[18:33], v[234:237], v[184:187], v[18:33]
	s_waitcnt lgkmcnt(2)
	v_mfma_f32_32x32x16_bf16 v[2:17], v[244:247], v[184:187], v[2:17]
	s_waitcnt lgkmcnt(1)
	v_mfma_f32_32x32x16_bf16 v[18:33], v[196:199], v[188:191], v[18:33]
	s_waitcnt lgkmcnt(0)
	v_mfma_f32_32x32x16_bf16 v[2:17], v[200:203], v[188:191], v[2:17]
	v_add_f32_e32 v0, v172, v176
	v_add_f32_e32 v161, v161, v0
	v_permlane32_swap_b32 v248, v249
	v_max_f32_e32 v174, v248, v249
	s_setprio 0
	s_cmp_lg_u32 s32, 0
	s_cbranch_scc1 .Lfb_b1
	s_waitcnt lgkmcnt(0)
	s_barrier

; DI float fexp2(float x) { return __builtin_amdgcn_exp2f(x); }
; template <int DK, int DV, int MODE> ...
;     ...
;     const float mabs = mx + mbase;
;     if (__any(mabs > mrun + ATT_THR)) {
;       const float mn = fmaxf(mrun, mabs), alpha = fexp2(mrun - mn); mrun = mn; lsum *= alpha;
; #pragma unroll
;       for (int db = 0; db < DV / 32; ++db)
; #pragma unroll
;         for (int i = 0; i < 16; ++i) O[db][i] *= alpha;
;     }
;     const float delta = mrun - mbase;
;     if (__any(delta != 0.f)) {
; #pragma unroll
;       for (int kb = 0; kb < 2; ++kb)
; #pragma unroll
;         for (int i = 0; i < 16; ++i) st[kb][i] -= delta;
;     }
.Lf_resc_a:
	v_max_f32_e32 v0, v66, v66
	v_max_f32_e32 v66, v143, v143
	v_max_f32_e32 v66, v66, v0
	v_sub_f32_e32 v0, v143, v66
	v_exp_f32_e32 v0, v0
	v_mov_b32_e32 v143, v66
	v_mul_f32_e32 v161, v161, v0
	v_pk_mul_f32 v[16:17], v[16:17], v[0:1] op_sel_hi:[1,0]
	v_pk_mul_f32 v[14:15], v[14:15], v[0:1] op_sel_hi:[1,0]
	v_pk_mul_f32 v[12:13], v[12:13], v[0:1] op_sel_hi:[1,0]
	v_pk_mul_f32 v[10:11], v[10:11], v[0:1] op_sel_hi:[1,0]
	v_pk_mul_f32 v[8:9], v[8:9], v[0:1] op_sel_hi:[1,0]
	v_pk_mul_f32 v[6:7], v[6:7], v[0:1] op_sel_hi:[1,0]
	v_pk_mul_f32 v[4:5], v[4:5], v[0:1] op_sel_hi:[1,0]
	v_pk_mul_f32 v[2:3], v[2:3], v[0:1] op_sel_hi:[1,0]
	v_pk_mul_f32 v[32:33], v[32:33], v[0:1] op_sel_hi:[1,0]
	v_pk_mul_f32 v[30:31], v[30:31], v[0:1] op_sel_hi:[1,0]
	v_pk_mul_f32 v[28:29], v[28:29], v[0:1] op_sel_hi:[1,0]
	v_pk_mul_f32 v[26:27], v[26:27], v[0:1] op_sel_hi:[1,0]
	v_pk_mul_f32 v[24:25], v[24:25], v[0:1] op_sel_hi:[1,0]
	v_pk_mul_f32 v[22:23], v[22:23], v[0:1] op_sel_hi:[1,0]
	v_pk_mul_f32 v[20:21], v[20:21], v[0:1] op_sel_hi:[1,0]
	v_pk_mul_f32 v[18:19], v[18:19], v[0:1] op_sel_hi:[1,0]
	s_branch .Lf_ra
.Lf_delta_a:
	v_pk_add_f32 v[50:51], v[50:51], v[0:1] op_sel_hi:[1,0] neg_lo:[0,1] neg_hi:[0,1]
	v_pk_add_f32 v[52:53], v[52:53], v[0:1] op_sel_hi:[1,0] neg_lo:[0,1] neg_hi:[0,1]
	v_pk_add_f32 v[54:55], v[54:55], v[0:1] op_sel_hi:[1,0] neg_lo:[0,1] neg_hi:[0,1]
	v_pk_add_f32 v[56:57], v[56:57], v[0:1] op_sel_hi:[1,0] neg_lo:[0,1] neg_hi:[0,1]
	v_pk_add_f32 v[58:59], v[58:59], v[0:1] op_sel_hi:[1,0] neg_lo:[0,1] neg_hi:[0,1]
	v_pk_add_f32 v[60:61], v[60:61], v[0:1] op_sel_hi:[1,0] neg_lo:[0,1] neg_hi:[0,1]
	v_pk_add_f32 v[62:63], v[62:63], v[0:1] op_sel_hi:[1,0] neg_lo:[0,1] neg_hi:[0,1]
	v_pk_add_f32 v[64:65], v[64:65], v[0:1] op_sel_hi:[1,0] neg_lo:[0,1] neg_hi:[0,1]
	v_pk_add_f32 v[34:35], v[34:35], v[0:1] op_sel_hi:[1,0] neg_lo:[0,1] neg_hi:[0,1]
	v_pk_add_f32 v[36:37], v[36:37], v[0:1] op_sel_hi:[1,0] neg_lo:[0,1] neg_hi:[0,1]
	v_pk_add_f32 v[38:39], v[38:39], v[0:1] op_sel_hi:[1,0] neg_lo:[0,1] neg_hi:[0,1]
	v_pk_add_f32 v[40:41], v[40:41], v[0:1] op_sel_hi:[1,0] neg_lo:[0,1] neg_hi:[0,1]
	v_pk_add_f32 v[42:43], v[42:43], v[0:1] op_sel_hi:[1,0] neg_lo:[0,1] neg_hi:[0,1]
	v_pk_add_f32 v[44:45], v[44:45], v[0:1] op_sel_hi:[1,0] neg_lo:[0,1] neg_hi:[0,1]
	v_pk_add_f32 v[46:47], v[46:47], v[0:1] op_sel_hi:[1,0] neg_lo:[0,1] neg_hi:[0,1]
	v_pk_add_f32 v[48:49], v[48:49], v[0:1] op_sel_hi:[1,0] neg_lo:[0,1] neg_hi:[0,1]
	s_branch .Lf_da
.Lf_resc_b:
	v_max_f32_e32 v0, v34, v34
	v_max_f32_e32 v34, v143, v143
	v_max_f32_e32 v34, v34, v0
	v_sub_f32_e32 v0, v143, v34
	v_exp_f32_e32 v0, v0
	v_mov_b32_e32 v143, v34
	v_mul_f32_e32 v161, v161, v0
	v_pk_mul_f32 v[16:17], v[16:17], v[0:1] op_sel_hi:[1,0]
	v_pk_mul_f32 v[14:15], v[14:15], v[0:1] op_sel_hi:[1,0]
	v_pk_mul_f32 v[12:13], v[12:13], v[0:1] op_sel_hi:[1,0]
	v_pk_mul_f32 v[10:11], v[10:11], v[0:1] op_sel_hi:[1,0]
	v_pk_mul_f32 v[8:9], v[8:9], v[0:1] op_sel_hi:[1,0]
	v_pk_mul_f32 v[6:7], v[6:7], v[0:1] op_sel_hi:[1,0]
	v_pk_mul_f32 v[4:5], v[4:5], v[0:1] op_sel_hi:[1,0]
	v_pk_mul_f32 v[2:3], v[2:3], v[0:1] op_sel_hi:[1,0]
	v_pk_mul_f32 v[32:33], v[32:33], v[0:1] op_sel_hi:[1,0]
	v_pk_mul_f32 v[30:31], v[30:31], v[0:1] op_sel_hi:[1,0]
	v_pk_mul_f32 v[28:29], v[28:29], v[0:1] op_sel_hi:[1,0]
	v_pk_mul_f32 v[26:27], v[26:27], v[0:1] op_sel_hi:[1,0]
	v_pk_mul_f32 v[24:25], v[24:25], v[0:1] op_sel_hi:[1,0]
	v_pk_mul_f32 v[22:23], v[22:23], v[0:1] op_sel_hi:[1,0]
	v_pk_mul_f32 v[20:21], v[20:21], v[0:1] op_sel_hi:[1,0]
	v_pk_mul_f32 v[18:19], v[18:19], v[0:1] op_sel_hi:[1,0]
	s_branch .Lf_rb
.Lf_delta_b:
	v_pk_add_f32 v[82:83], v[82:83], v[0:1] op_sel_hi:[1,0] neg_lo:[0,1] neg_hi:[0,1]
	v_pk_add_f32 v[84:85], v[84:85], v[0:1] op_sel_hi:[1,0] neg_lo:[0,1] neg_hi:[0,1]
	v_pk_add_f32 v[86:87], v[86:87], v[0:1] op_sel_hi:[1,0] neg_lo:[0,1] neg_hi:[0,1]
	v_pk_add_f32 v[88:89], v[88:89], v[0:1] op_sel_hi:[1,0] neg_lo:[0,1] neg_hi:[0,1]
	v_pk_add_f32 v[90:91], v[90:91], v[0:1] op_sel_hi:[1,0] neg_lo:[0,1] neg_hi:[0,1]
	v_pk_add_f32 v[92:93], v[92:93], v[0:1] op_sel_hi:[1,0] neg_lo:[0,1] neg_hi:[0,1]
	v_pk_add_f32 v[94:95], v[94:95], v[0:1] op_sel_hi:[1,0] neg_lo:[0,1] neg_hi:[0,1]
	v_pk_add_f32 v[96:97], v[96:97], v[0:1] op_sel_hi:[1,0] neg_lo:[0,1] neg_hi:[0,1]
	v_pk_add_f32 v[66:67], v[66:67], v[0:1] op_sel_hi:[1,0] neg_lo:[0,1] neg_hi:[0,1]
	v_pk_add_f32 v[68:69], v[68:69], v[0:1] op_sel_hi:[1,0] neg_lo:[0,1] neg_hi:[0,1]
	v_pk_add_f32 v[70:71], v[70:71], v[0:1] op_sel_hi:[1,0] neg_lo:[0,1] neg_hi:[0,1]
	v_pk_add_f32 v[72:73], v[72:73], v[0:1] op_sel_hi:[1,0] neg_lo:[0,1] neg_hi:[0,1]
	v_pk_add_f32 v[74:75], v[74:75], v[0:1] op_sel_hi:[1,0] neg_lo:[0,1] neg_hi:[0,1]
	v_pk_add_f32 v[76:77], v[76:77], v[0:1] op_sel_hi:[1,0] neg_lo:[0,1] neg_hi:[0,1]
	v_pk_add_f32 v[78:79], v[78:79], v[0:1] op_sel_hi:[1,0] neg_lo:[0,1] neg_hi:[0,1]
	v_pk_add_f32 v[80:81], v[80:81], v[0:1] op_sel_hi:[1,0] neg_lo:[0,1] neg_hi:[0,1]
	s_branch .Lf_db

; template <int DK, int DV, int MODE> ...
;     ...
;       const int d0 = rel0 + 64 * t;
;       if (!(d0 - 31 >= 91) && !(d0 + 63 <= -91)) {
;     ...
;   for (int t = 0; t < ntiles; t += 2) {
;     FA_STEP(t, stA, baseA, stB, baseB, false);
;     if (t + 1 < ntiles) FA_STEP(t + 1, stB, baseB, stA, baseA, true);
;   }
.Lstg_post4:
.LBB0_250:
	s_mov_b64 s[22:23], 0x60000
	s_add_i32 s19, s19, 2
	s_addk_i32 s18, 0x80
	v_lshl_add_u64 v[138:139], v[138:139], 0, s[22:23]
	s_cmp_lt_u32 s20, s17
	v_lshl_add_u64 v[140:141], v[140:141], 0, s[22:23]
	s_cbranch_scc0 .LBB0_223
.LBB0_251:
	s_cmp_lt_u32 s19, s17
	s_cbranch_scc0 .Lmla_slow
	s_cmp_eq_u32 s18, 0
	s_cbranch_scc1 .Lmla_slow
	v_add_u32_e32 v167, s18, v165
	v_add_u32_e32 v0, 0xffffff86, v167
	v_cmp_lt_u32_e32 vcc, 0xfffffeac, v0
	s_cbranch_vccz .Lmla_fast
